# P0 rmsnorm loop: loop-invariant norm-weight loads hoisted out of the loop (removes three load+store drains per iteration)
# baseline (speedup 1.0000x reference)
; __device__ __forceinline__ float wave_sum(float v) {
; #pragma unroll
;     for (int o = 1; o < 64; o <<= 1) v += __shfl_xor(v, o);
;     return v;
; }
; __device__ __forceinline__ void p0_prologue(const Ptrs& P, LAS unsigned char* lds, int vcu, int G) {
;     ...
;     for (int m = gw; m < TT; m += 2 * NGW) {
;         const int m2 = (m + NGW < TT) ? m + NGW : m;
;         const f32x4* xr = (const f32x4*)(P.x + (size_t)m * DM) + lane; const f32x4* xr2 = (const f32x4*)(P.x + (size_t)m2 * DM) + lane; f32x4 v[4], v2[4]; float s = 0.f, s2 = 0.f;
; #pragma unroll
;         for (int j = 0; j < 4; ++j) { v[j] = xr[64 * j]; v2[j] = xr2[64 * j]; }
; #pragma unroll
;         for (int j = 0; j < 4; ++j) { s += (v[j].x * v[j].x + v[j].y * v[j].y) + (v[j].z * v[j].z + v[j].w * v[j].w); s2 += (v2[j].x * v2[j].x + v2[j].y * v2[j].y) + (v2[j].z * v2[j].z + v2[j].w * v2[j].w); }
;         const float rstd = rsqrtf(wave_sum(s) * (1.0f / DM) + NORM_EPS), rstd2 = rsqrtf(wave_sum(s2) * (1.0f / DM) + NORM_EPS);
;         u32x2* o8 = (u32x2*)(H + (size_t)m * DM) + lane; u32x2* o82 = (u32x2*)(H + (size_t)m2 * DM) + lane;
; #pragma unroll
;         for (int j = 0; j < 4; ++j) { const f32x4 w4 = ((const f32x4*)P.norm_w)[lane + 64 * j];
.LBB0_55:
	s_cmpk_gt_i32 s0, 0x3fff
	s_cbranch_scc1 .LBB0_58
	v_mbcnt_lo_u32_b32 v6, -1, 0
	v_mbcnt_hi_u32_b32 v6, -1, v6
	v_and_b32_e32 v7, 64, v6
	v_add_u32_e32 v12, 64, v7
	v_xor_b32_e32 v7, 1, v6
	v_cmp_lt_i32_e32 vcc, v7, v12
	v_xor_b32_e32 v8, 2, v6
	v_xor_b32_e32 v9, 4, v6
	v_cndmask_b32_e32 v7, v6, v7, vcc
	v_cmp_lt_i32_e32 vcc, v8, v12
	v_xor_b32_e32 v10, 8, v6
	v_xor_b32_e32 v11, 16, v6
	v_cndmask_b32_e32 v8, v6, v8, vcc
	v_cmp_lt_i32_e32 vcc, v9, v12
	v_xor_b32_e32 v13, 32, v6
	v_lshlrev_b32_e32 v4, 3, v25
	v_cndmask_b32_e32 v9, v6, v9, vcc
	v_cmp_lt_i32_e32 vcc, v10, v12
	v_mov_b32_e32 v5, 0
	v_lshl_add_u64 v[0:1], s[78:79], 0, v[4:5]
	v_cndmask_b32_e32 v10, v6, v10, vcc
	v_cmp_lt_i32_e32 vcc, v11, v12
	s_mov_b64 s[6:7], 0x2000000
	v_lshlrev_b32_e32 v4, 4, v25
	v_cndmask_b32_e32 v11, v6, v11, vcc
	v_cmp_lt_i32_e32 vcc, v13, v12
	v_lshl_add_u64 v[0:1], v[0:1], 0, s[6:7]
	s_waitcnt lgkmcnt(0)
	v_lshl_add_u64 v[2:3], s[56:57], 0, v[4:5]
	v_cndmask_b32_e32 v6, v6, v13, vcc
	v_lshl_add_u64 v[4:5], s[60:61], 0, v[4:5]
	v_lshlrev_b32_e32 v7, 2, v7
	v_lshlrev_b32_e32 v8, 2, v8
	v_lshlrev_b32_e32 v9, 2, v9
	v_lshlrev_b32_e32 v10, 2, v10
	v_lshlrev_b32_e32 v11, 2, v11
	v_lshlrev_b32_e32 v12, 2, v6
	s_mov_b32 s6, 0x3a800000
	v_mov_b32_e32 v6, 0x358637bd
	s_mov_b32 s7, 0x800000
	global_load_dwordx4 v[100:103], v[4:5], off
	global_load_dwordx4 v[104:107], v[4:5], off offset:1024
	global_load_dwordx4 v[108:111], v[4:5], off offset:2048
	global_load_dwordx4 v[112:115], v[4:5], off offset:3072
.LBB0_57:
	s_add_i32 s8, s0, s17
	s_cmpk_lt_i32 s8, 0x4000
	s_cselect_b32 s10, s8, s0
	s_ashr_i32 s1, s0, 31
	s_lshl_b64 s[12:13], s[0:1], 12
	s_ashr_i32 s11, s10, 31
	v_lshl_add_u64 v[22:23], v[2:3], 0, s[12:13]
	s_lshl_b64 s[12:13], s[10:11], 12
	global_load_dwordx4 v[18:21], v[22:23], off nt
	global_load_dwordx4 v[26:29], v[22:23], off offset:1024 nt
	global_load_dwordx4 v[30:33], v[22:23], off offset:3072 nt
	global_load_dwordx4 v[34:37], v[22:23], off offset:2048 nt
	v_lshl_add_u64 v[22:23], v[2:3], 0, s[12:13]
	global_load_dwordx4 v[38:41], v[22:23], off nt
	global_load_dwordx4 v[42:45], v[22:23], off offset:1024 nt
	global_load_dwordx4 v[46:49], v[22:23], off offset:3072 nt
	global_load_dwordx4 v[50:53], v[22:23], off offset:2048 nt
	s_lshl_b64 s[0:1], s[0:1], 11
	v_lshl_add_u64 v[54:55], v[0:1], 0, s[0:1]
	s_lshl_b64 s[0:1], s[10:11], 11
	v_lshl_add_u64 v[56:57], v[0:1], 0, s[0:1]
	s_waitcnt vmcnt(7)
	v_pk_mul_f32 v[22:23], v[20:21], v[20:21]
	v_pk_mul_f32 v[58:59], v[18:19], v[18:19]
	s_waitcnt vmcnt(6)
	v_pk_mul_f32 v[60:61], v[28:29], v[28:29]
	v_pk_mul_f32 v[62:63], v[26:27], v[26:27]
	s_waitcnt vmcnt(4)
	v_mul_f32_e32 v64, v35, v35
	v_mul_f32_e32 v66, v37, v37
	v_pk_mov_b32 v[68:69], v[58:59], v[22:23] op_sel:[1,0]
	v_mov_b32_e32 v59, v23
	s_waitcnt vmcnt(3)
	v_pk_mul_f32 v[22:23], v[40:41], v[40:41]
	v_pk_mul_f32 v[70:71], v[38:39], v[38:39]
	v_pk_mov_b32 v[72:73], v[62:63], v[60:61] op_sel:[1,0]
	v_mov_b32_e32 v63, v61
	s_waitcnt vmcnt(2)
	v_pk_mul_f32 v[60:61], v[44:45], v[44:45]
	v_pk_mul_f32 v[74:75], v[42:43], v[42:43]
	v_mul_f32_e32 v77, v32, v32
	v_mul_f32_e32 v79, v33, v33
	v_pk_fma_f32 v[64:65], v[34:35], v[34:35], v[64:65] op_sel_hi:[1,1,0]
	v_pk_fma_f32 v[66:67], v[36:37], v[36:37], v[66:67] op_sel_hi:[1,1,0]
	v_pk_add_f32 v[58:59], v[68:69], v[58:59]
	v_pk_mov_b32 v[68:69], v[70:71], v[22:23] op_sel:[1,0]
	v_mov_b32_e32 v71, v23
	v_pk_add_f32 v[22:23], v[72:73], v[62:63]
	v_pk_mov_b32 v[62:63], v[74:75], v[60:61] op_sel:[1,0]
	v_mov_b32_e32 v75, v61
	s_waitcnt vmcnt(0)
	v_mul_f32_e32 v76, v51, v51
	v_mul_f32_e32 v78, v53, v53
	v_mov_b32_e32 v65, v77
	v_mov_b32_e32 v67, v79
	v_pk_add_f32 v[68:69], v[68:69], v[70:71]
	v_pk_add_f32 v[62:63], v[62:63], v[74:75]
	v_mul_f32_e32 v13, v30, v30
	v_mul_f32_e32 v25, v31, v31
	v_mul_f32_e32 v80, v46, v46
	v_mul_f32_e32 v81, v47, v47
	v_mul_f32_e32 v82, v48, v48
	v_mul_f32_e32 v83, v49, v49
	v_pk_fma_f32 v[60:61], v[50:51], v[50:51], v[76:77] op_sel_hi:[1,1,0]
	v_pk_fma_f32 v[72:73], v[52:53], v[52:53], v[78:79] op_sel_hi:[1,1,0]
	v_pk_add_f32 v[58:59], v[58:59], v[58:59] op_sel:[0,1] op_sel_hi:[1,0]
	v_pk_add_f32 v[22:23], v[22:23], v[22:23] op_sel:[0,1] op_sel_hi:[1,0]
	v_pk_add_f32 v[64:65], v[64:65], v[66:67]
	v_pk_add_f32 v[66:67], v[68:69], v[68:69] op_sel:[0,1] op_sel_hi:[1,0]
	v_pk_add_f32 v[62:63], v[62:63], v[62:63] op_sel:[0,1] op_sel_hi:[1,0]
	v_mov_b32_e32 v61, v82
	v_mov_b32_e32 v73, v83
	v_mov_b32_e32 v59, v13
	v_mov_b32_e32 v23, v25
	v_mov_b32_e32 v67, v80
	v_mov_b32_e32 v63, v81
	v_pk_add_f32 v[60:61], v[60:61], v[72:73]
	v_pk_add_f32 v[22:23], v[58:59], v[22:23]
	v_pk_add_f32 v[58:59], v[66:67], v[62:63]
	v_pk_add_f32 v[22:23], v[22:23], v[64:65]
	v_pk_add_f32 v[58:59], v[58:59], v[60:61]
	v_mov_b32_e32 v61, v22
	v_mov_b32_e32 v60, v58
	v_mov_b32_e32 v22, v59
	v_pk_add_f32 v[22:23], v[60:61], v[22:23]
	ds_bpermute_b32 v59, v7, v23
	ds_bpermute_b32 v58, v7, v22
	s_waitcnt lgkmcnt(0)
; __device__ __forceinline__ unsigned pk_bf16(float lo, float hi) { typedef __bf16 b2 __attribute__((ext_vector_type(2))); f32x2 v = {lo, hi}; b2 b = __builtin_convertvector(v, b2); return __builtin_bit_cast(unsigned, b); }
; __device__ __forceinline__ void p0_prologue(const Ptrs& P, LAS unsigned char* lds, int vcu, int G) {
;     ...
;         const float rstd = rsqrtf(wave_sum(s) * (1.0f / DM) + NORM_EPS), rstd2 = rsqrtf(wave_sum(s2) * (1.0f / DM) + NORM_EPS);
;         u32x2* o8 = (u32x2*)(H + (size_t)m * DM) + lane; u32x2* o82 = (u32x2*)(H + (size_t)m2 * DM) + lane;
; #pragma unroll
;         for (int j = 0; j < 4; ++j) { const f32x4 w4 = ((const f32x4*)P.norm_w)[lane + 64 * j];
;             o8[64 * j] = (u32x2){pk_bf16(v[j].x * rstd * w4.x, v[j].y * rstd * w4.y), pk_bf16(v[j].z * rstd * w4.z, v[j].w * rstd * w4.w)};
;             o82[64 * j] = (u32x2){pk_bf16(v2[j].x * rstd2 * w4.x, v2[j].y * rstd2 * w4.y), pk_bf16(v2[j].z * rstd2 * w4.z, v2[j].w * rstd2 * w4.w)}; }
	v_pk_add_f32 v[22:23], v[22:23], v[58:59]
	ds_bpermute_b32 v59, v8, v23
	ds_bpermute_b32 v58, v8, v22
	s_waitcnt lgkmcnt(0)
	v_pk_add_f32 v[22:23], v[22:23], v[58:59]
	ds_bpermute_b32 v59, v9, v23
	ds_bpermute_b32 v58, v9, v22
	s_waitcnt lgkmcnt(0)
	v_pk_add_f32 v[22:23], v[22:23], v[58:59]
	ds_bpermute_b32 v59, v10, v23
	ds_bpermute_b32 v58, v10, v22
	s_waitcnt lgkmcnt(0)
	v_pk_add_f32 v[22:23], v[22:23], v[58:59]
	ds_bpermute_b32 v59, v11, v23
	ds_bpermute_b32 v58, v11, v22
	s_waitcnt lgkmcnt(0)
	v_pk_add_f32 v[22:23], v[22:23], v[58:59]
	ds_bpermute_b32 v59, v12, v23
	ds_bpermute_b32 v58, v12, v22
	s_waitcnt lgkmcnt(0)
	v_pk_add_f32 v[22:23], v[22:23], v[58:59]
	s_nop 0
	v_pk_fma_f32 v[22:23], v[22:23], s[6:7], v[6:7] op_sel_hi:[1,0,0]
	s_nop 0
	v_mul_f32_e32 v13, 0x4b800000, v23
	v_cmp_gt_f32_e64 s[0:1], s7, v23
	v_mul_f32_e32 v25, 0x4b800000, v22
	v_cmp_gt_f32_e32 vcc, s7, v22
	v_cndmask_b32_e64 v13, v23, v13, s[0:1]
	v_rsq_f32_e32 v13, v13
	v_cndmask_b32_e32 v22, v22, v25, vcc
	v_rsq_f32_e32 v23, v22
	v_mul_f32_e32 v22, 0x45800000, v13
	v_cndmask_b32_e64 v22, v13, v22, s[0:1]
	v_mul_f32_e32 v25, 0x45800000, v23
	v_cndmask_b32_e32 v58, v23, v25, vcc
	v_pk_mul_f32 v[18:19], v[18:19], v[22:23] op_sel_hi:[1,0]
	v_pk_mul_f32 v[20:21], v[20:21], v[22:23] op_sel_hi:[1,0]
	v_pk_mul_f32 v[38:39], v[38:39], v[58:59] op_sel_hi:[1,0]
	v_pk_mul_f32 v[40:41], v[40:41], v[58:59] op_sel_hi:[1,0]
	v_pk_mul_f32 v[18:19], v[100:101], v[18:19]
	v_pk_mul_f32 v[20:21], v[102:103], v[20:21]
	v_pk_mul_f32 v[14:15], v[100:101], v[38:39]
	v_pk_mul_f32 v[16:17], v[102:103], v[40:41]
	v_cvt_pk_bf16_f32 v18, v18, v19
	v_cvt_pk_bf16_f32 v19, v20, v21
	v_cvt_pk_bf16_f32 v14, v14, v15
	v_cvt_pk_bf16_f32 v15, v16, v17
	global_store_dwordx2 v[54:55], v[18:19], off
	global_store_dwordx2 v[56:57], v[14:15], off
	v_pk_mul_f32 v[18:19], v[26:27], v[22:23] op_sel_hi:[1,0]
	v_pk_mul_f32 v[20:21], v[28:29], v[22:23] op_sel_hi:[1,0]
	v_pk_mul_f32 v[26:27], v[42:43], v[58:59] op_sel_hi:[1,0]
	v_pk_mul_f32 v[28:29], v[44:45], v[58:59] op_sel_hi:[1,0]
	s_add_i32 s0, s8, s17
	s_cmpk_gt_i32 s0, 0x3fff
	v_pk_mul_f32 v[18:19], v[104:105], v[18:19]
	v_pk_mul_f32 v[20:21], v[106:107], v[20:21]
	v_pk_mul_f32 v[14:15], v[104:105], v[26:27]
	v_pk_mul_f32 v[16:17], v[106:107], v[28:29]
	v_cvt_pk_bf16_f32 v18, v18, v19
	v_cvt_pk_bf16_f32 v19, v20, v21
	v_cvt_pk_bf16_f32 v14, v14, v15
	v_cvt_pk_bf16_f32 v15, v16, v17
	global_store_dwordx2 v[54:55], v[18:19], off offset:512
	global_store_dwordx2 v[56:57], v[14:15], off offset:512
	v_pk_mul_f32 v[18:19], v[34:35], v[22:23] op_sel_hi:[1,0]
	v_pk_mul_f32 v[20:21], v[36:37], v[22:23] op_sel_hi:[1,0]
	v_pk_mul_f32 v[26:27], v[50:51], v[58:59] op_sel_hi:[1,0]
	v_pk_mul_f32 v[28:29], v[52:53], v[58:59] op_sel_hi:[1,0]
	v_pk_mul_f32 v[18:19], v[18:19], v[108:109]
	v_pk_mul_f32 v[20:21], v[20:21], v[110:111]
	v_pk_mul_f32 v[14:15], v[108:109], v[26:27]
	v_pk_mul_f32 v[16:17], v[110:111], v[28:29]
	v_cvt_pk_bf16_f32 v18, v18, v19
	v_cvt_pk_bf16_f32 v19, v20, v21
	v_cvt_pk_bf16_f32 v14, v14, v15
	v_cvt_pk_bf16_f32 v15, v16, v17
	global_store_dwordx2 v[54:55], v[18:19], off offset:1024
	global_store_dwordx2 v[56:57], v[14:15], off offset:1024
	v_pk_mul_f32 v[18:19], v[30:31], v[22:23] op_sel_hi:[1,0]
	v_pk_mul_f32 v[20:21], v[32:33], v[22:23] op_sel_hi:[1,0]
	v_pk_mul_f32 v[22:23], v[46:47], v[58:59] op_sel_hi:[1,0]
	v_pk_mul_f32 v[26:27], v[48:49], v[58:59] op_sel_hi:[1,0]
	v_pk_mul_f32 v[18:19], v[18:19], v[112:113]
	v_pk_mul_f32 v[20:21], v[20:21], v[114:115]
	v_pk_mul_f32 v[14:15], v[22:23], v[112:113]
	v_pk_mul_f32 v[16:17], v[26:27], v[114:115]
	v_cvt_pk_bf16_f32 v18, v18, v19
	v_cvt_pk_bf16_f32 v19, v20, v21
	v_cvt_pk_bf16_f32 v14, v14, v15
	v_cvt_pk_bf16_f32 v15, v16, v17
	global_store_dwordx2 v[54:55], v[18:19], off offset:1536
	global_store_dwordx2 v[56:57], v[14:15], off offset:1536
	s_cbranch_scc0 .LBB0_57
